# G5 residual epilogue: gate vector loaded once, all eight residual rows requested up front, row steps run under counted waits
# speedup vs baseline: 1.0106x; 1.0037x over previous
.LBB0_137:
	s_or_b64 exec, exec, s[20:21]
	s_movk_i32 s8, 0x4400
	v_mul_lo_u32 v4, v136, s8
	v_lshl_or_b32 v2, v138, 2, v4
	s_movk_i32 s8, 0x440
	v_mad_u32_u24 v2, v135, s8, v2
	v_add_u32_e32 v5, 0x1000, v2
	v_add_u32_e32 v6, 0x1400, v2
	s_waitcnt vmcnt(0) lgkmcnt(0)
	s_barrier
	ds_write2_b32 v2, v102, v90 offset1:16
	ds_write2_b32 v2, v103, v91 offset0:68 offset1:84
	ds_write2_b32 v2, v104, v92 offset0:136 offset1:152
	ds_write2_b32 v2, v105, v93 offset0:204 offset1:220
	ds_write2_b32 v2, v74, v94 offset0:32 offset1:48
	ds_write2_b32 v2, v75, v95 offset0:100 offset1:116
	ds_write2_b32 v2, v76, v96 offset0:168 offset1:184
	ds_write2_b32 v2, v77, v97 offset0:236 offset1:252
	ds_write2_b32 v5, v98, v78 offset0:64 offset1:80
	ds_write2_b32 v5, v99, v79 offset0:132 offset1:148
	ds_write2_b32 v5, v100, v80 offset0:200 offset1:216
	ds_write2_b32 v6, v101, v81 offset0:12 offset1:28
	ds_write2_b32 v5, v58, v82 offset0:96 offset1:112
	ds_write2_b32 v5, v59, v83 offset0:164 offset1:180
	ds_write2_b32 v5, v60, v84 offset0:232 offset1:248
	ds_write2_b32 v6, v61, v85 offset0:44 offset1:60
	v_add_u32_e32 v5, 0x2000, v2
	v_add_u32_e32 v6, 0x2400, v2
	ds_write2_b32 v5, v86, v62 offset0:128 offset1:144
	ds_write2_b32 v5, v87, v63 offset0:196 offset1:212
	ds_write2_b32 v6, v88, v64 offset0:8 offset1:24
	ds_write2_b32 v6, v89, v65 offset0:76 offset1:92
	ds_write2_b32 v5, v38, v66 offset0:160 offset1:176
	ds_write2_b32 v5, v39, v67 offset0:228 offset1:244
	ds_write2_b32 v6, v40, v68 offset0:40 offset1:56
	ds_write2_b32 v6, v41, v69 offset0:108 offset1:124
	v_add_u32_e32 v5, 0x3000, v2
	v_add_u32_e32 v2, 0x3400, v2
	v_readlane_b32 s8, v254, 46
	ds_write2_b32 v5, v70, v50 offset0:192 offset1:208
	ds_write2_b32 v2, v71, v51 offset0:4 offset1:20
	ds_write2_b32 v2, v72, v52 offset0:72 offset1:88
	ds_write2_b32 v2, v73, v53 offset0:140 offset1:156
	ds_write2_b32 v5, v30, v34 offset0:224 offset1:240
	ds_write2_b32 v2, v31, v35 offset0:36 offset1:52
	ds_write2_b32 v2, v32, v36 offset0:104 offset1:120
	ds_write2_b32 v2, v33, v37 offset0:172 offset1:188
	v_lshl_add_u32 v0, v0, 6, s8
	v_lshrrev_b32_e32 v5, 3, v134
	v_lshlrev_b32_e32 v2, 3, v134
	v_and_b32_e32 v6, 56, v2
	v_or_b32_e32 v2, v0, v5
	v_add_u32_e32 v0, 0xfffff000, v0
	v_lshlrev_b32_e32 v3, 6, v139
	v_readlane_b32 s8, v254, 47
	v_lshrrev_b32_e32 v9, 10, v0
	v_cmp_lt_i32_e32 vcc, s1, v2
	v_or3_b32 v12, v3, s8, v6
	v_mul_u32_u24_e32 v3, 0x110, v5
	v_lshlrev_b32_e32 v5, 2, v6
	v_cndmask_b32_e32 v0, 4, v9, vcc
	s_mul_i32 s8, s18, 5
	v_add3_u32 v8, v4, v3, v5
	v_add_u32_e32 v0, s8, v0
	v_mov_b64_e32 v[4:5], s[14:15]
	v_mad_i64_i32 v[6:7], s[20:21], v0, s82, v[4:5]
	v_lshlrev_b32_e32 v0, 2, v12
	v_ashrrev_i32_e32 v3, 31, v2
	v_lshl_add_u64 v[18:19], v[6:7], 0, v[0:1]
	v_lshlrev_b64 v[6:7], 11, v[2:3]
	v_lshl_add_u64 v[10:11], s[66:67], 0, v[6:7]
	v_lshlrev_b32_e32 v6, 1, v12
	v_mov_b32_e32 v7, v1
	v_lshl_add_u64 v[26:27], v[10:11], 0, v[6:7]
	s_mov_b64 s[22:23], 0x8605000
	v_lshl_add_u64 v[18:19], v[18:19], 0, s[22:23]
	global_load_dwordx4 v[36:39], v[18:19], off
	global_load_dwordx4 v[40:43], v[18:19], off offset:16
	global_load_dwordx4 v[44:47], v[26:27], off
	v_or_b32_e32 v10, 8, v2
	v_ashrrev_i32_e32 v11, 31, v10
	v_lshlrev_b64 v[10:11], 11, v[10:11]
	v_lshl_add_u64 v[10:11], s[66:67], 0, v[10:11]
	v_lshl_add_u64 v[102:103], v[10:11], 0, v[6:7]
	global_load_dwordx4 v[48:51], v[102:103], off
	v_or_b32_e32 v10, 16, v2
	v_ashrrev_i32_e32 v11, 31, v10
	v_lshlrev_b64 v[10:11], 11, v[10:11]
	v_lshl_add_u64 v[10:11], s[66:67], 0, v[10:11]
	v_lshl_add_u64 v[104:105], v[10:11], 0, v[6:7]
	global_load_dwordx4 v[52:55], v[104:105], off
	v_or_b32_e32 v10, 24, v2
	v_ashrrev_i32_e32 v11, 31, v10
	v_lshlrev_b64 v[10:11], 11, v[10:11]
	v_lshl_add_u64 v[10:11], s[66:67], 0, v[10:11]
	v_lshl_add_u64 v[106:107], v[10:11], 0, v[6:7]
	global_load_dwordx4 v[56:59], v[106:107], off
	v_or_b32_e32 v10, 32, v2
	v_ashrrev_i32_e32 v11, 31, v10
	v_lshlrev_b64 v[10:11], 11, v[10:11]
	v_lshl_add_u64 v[10:11], s[66:67], 0, v[10:11]
	v_lshl_add_u64 v[108:109], v[10:11], 0, v[6:7]
	global_load_dwordx4 v[60:63], v[108:109], off
	v_or_b32_e32 v10, 40, v2
	v_ashrrev_i32_e32 v11, 31, v10
	v_lshlrev_b64 v[10:11], 11, v[10:11]
	v_lshl_add_u64 v[10:11], s[66:67], 0, v[10:11]
	v_lshl_add_u64 v[110:111], v[10:11], 0, v[6:7]
	global_load_dwordx4 v[64:67], v[110:111], off
	v_or_b32_e32 v10, 48, v2
	v_ashrrev_i32_e32 v11, 31, v10
	v_lshlrev_b64 v[10:11], 11, v[10:11]
	v_lshl_add_u64 v[10:11], s[66:67], 0, v[10:11]
	v_lshl_add_u64 v[112:113], v[10:11], 0, v[6:7]
	global_load_dwordx4 v[68:71], v[112:113], off
	v_or_b32_e32 v10, 56, v2
	v_ashrrev_i32_e32 v11, 31, v10
	v_lshlrev_b64 v[10:11], 11, v[10:11]
	v_lshl_add_u64 v[10:11], s[66:67], 0, v[10:11]
	v_lshl_add_u64 v[114:115], v[10:11], 0, v[6:7]
	global_load_dwordx4 v[72:75], v[114:115], off
	ds_read_b128 v[84:87], v8
	ds_read_b128 v[88:91], v8 offset:16
	ds_read_b128 v[92:95], v8 offset:2176
	ds_read_b128 v[96:99], v8 offset:2192
	s_waitcnt vmcnt(7)
	v_lshlrev_b32_e32 v116, 16, v44
	v_and_b32_e32 v117, 0xffff0000, v44
	v_lshlrev_b32_e32 v118, 16, v45
	v_and_b32_e32 v119, 0xffff0000, v45
	v_lshlrev_b32_e32 v120, 16, v46
	v_and_b32_e32 v121, 0xffff0000, v46
	v_lshlrev_b32_e32 v122, 16, v47
	v_and_b32_e32 v123, 0xffff0000, v47
	s_waitcnt lgkmcnt(2)
	v_pk_fma_f32 v[116:117], v[84:85], v[36:37], v[116:117]
	v_pk_fma_f32 v[118:119], v[86:87], v[38:39], v[118:119]
	v_pk_fma_f32 v[120:121], v[88:89], v[40:41], v[120:121]
	v_pk_fma_f32 v[122:123], v[90:91], v[42:43], v[122:123]
	v_cvt_pk_bf16_f32 v132, v116, v117
	v_cvt_pk_bf16_f32 v133, v118, v119
	v_cvt_pk_bf16_f32 v134, v120, v121
	v_cvt_pk_bf16_f32 v135, v122, v123
	global_store_dwordx4 v[26:27], v[132:135], off
	ds_read_b128 v[84:87], v8 offset:4352
	ds_read_b128 v[88:91], v8 offset:4368
	s_waitcnt vmcnt(7)
	v_lshlrev_b32_e32 v124, 16, v48
	v_and_b32_e32 v125, 0xffff0000, v48
	v_lshlrev_b32_e32 v126, 16, v49
	v_and_b32_e32 v127, 0xffff0000, v49
	v_lshlrev_b32_e32 v128, 16, v50
	v_and_b32_e32 v129, 0xffff0000, v50
	v_lshlrev_b32_e32 v130, 16, v51
	v_and_b32_e32 v131, 0xffff0000, v51
	s_waitcnt lgkmcnt(2)
	v_pk_fma_f32 v[124:125], v[92:93], v[36:37], v[124:125]
	v_pk_fma_f32 v[126:127], v[94:95], v[38:39], v[126:127]
	v_pk_fma_f32 v[128:129], v[96:97], v[40:41], v[128:129]
	v_pk_fma_f32 v[130:131], v[98:99], v[42:43], v[130:131]
	v_cvt_pk_bf16_f32 v136, v124, v125
	v_cvt_pk_bf16_f32 v137, v126, v127
	v_cvt_pk_bf16_f32 v138, v128, v129
	v_cvt_pk_bf16_f32 v139, v130, v131
	global_store_dwordx4 v[102:103], v[136:139], off
	ds_read_b128 v[92:95], v8 offset:6528
	ds_read_b128 v[96:99], v8 offset:6544
	s_waitcnt vmcnt(7)
	v_lshlrev_b32_e32 v116, 16, v52
	v_and_b32_e32 v117, 0xffff0000, v52
	v_lshlrev_b32_e32 v118, 16, v53
	v_and_b32_e32 v119, 0xffff0000, v53
	v_lshlrev_b32_e32 v120, 16, v54
	v_and_b32_e32 v121, 0xffff0000, v54
	v_lshlrev_b32_e32 v122, 16, v55
	v_and_b32_e32 v123, 0xffff0000, v55
	s_waitcnt lgkmcnt(2)
	v_pk_fma_f32 v[116:117], v[84:85], v[36:37], v[116:117]
	v_pk_fma_f32 v[118:119], v[86:87], v[38:39], v[118:119]
	v_pk_fma_f32 v[120:121], v[88:89], v[40:41], v[120:121]
	v_pk_fma_f32 v[122:123], v[90:91], v[42:43], v[122:123]
	v_cvt_pk_bf16_f32 v132, v116, v117
	v_cvt_pk_bf16_f32 v133, v118, v119
	v_cvt_pk_bf16_f32 v134, v120, v121
	v_cvt_pk_bf16_f32 v135, v122, v123
	global_store_dwordx4 v[104:105], v[132:135], off
	ds_read_b128 v[84:87], v8 offset:8704
	ds_read_b128 v[88:91], v8 offset:8720
	s_waitcnt vmcnt(7)
	v_lshlrev_b32_e32 v124, 16, v56
	v_and_b32_e32 v125, 0xffff0000, v56
	v_lshlrev_b32_e32 v126, 16, v57
	v_and_b32_e32 v127, 0xffff0000, v57
	v_lshlrev_b32_e32 v128, 16, v58
	v_and_b32_e32 v129, 0xffff0000, v58
	v_lshlrev_b32_e32 v130, 16, v59
	v_and_b32_e32 v131, 0xffff0000, v59
	s_waitcnt lgkmcnt(2)
	v_pk_fma_f32 v[124:125], v[92:93], v[36:37], v[124:125]
	v_pk_fma_f32 v[126:127], v[94:95], v[38:39], v[126:127]
	v_pk_fma_f32 v[128:129], v[96:97], v[40:41], v[128:129]
	v_pk_fma_f32 v[130:131], v[98:99], v[42:43], v[130:131]
	v_cvt_pk_bf16_f32 v136, v124, v125
	v_cvt_pk_bf16_f32 v137, v126, v127
	v_cvt_pk_bf16_f32 v138, v128, v129
	v_cvt_pk_bf16_f32 v139, v130, v131
	global_store_dwordx4 v[106:107], v[136:139], off
	ds_read_b128 v[92:95], v8 offset:10880
	ds_read_b128 v[96:99], v8 offset:10896
	s_waitcnt vmcnt(7)
	v_lshlrev_b32_e32 v116, 16, v60
	v_and_b32_e32 v117, 0xffff0000, v60
	v_lshlrev_b32_e32 v118, 16, v61
	v_and_b32_e32 v119, 0xffff0000, v61
	v_lshlrev_b32_e32 v120, 16, v62
	v_and_b32_e32 v121, 0xffff0000, v62
	v_lshlrev_b32_e32 v122, 16, v63
	v_and_b32_e32 v123, 0xffff0000, v63
	s_waitcnt lgkmcnt(2)
	v_pk_fma_f32 v[116:117], v[84:85], v[36:37], v[116:117]
	v_pk_fma_f32 v[118:119], v[86:87], v[38:39], v[118:119]
	v_pk_fma_f32 v[120:121], v[88:89], v[40:41], v[120:121]
	v_pk_fma_f32 v[122:123], v[90:91], v[42:43], v[122:123]
	v_cvt_pk_bf16_f32 v132, v116, v117
	v_cvt_pk_bf16_f32 v133, v118, v119
	v_cvt_pk_bf16_f32 v134, v120, v121
	v_cvt_pk_bf16_f32 v135, v122, v123
	global_store_dwordx4 v[108:109], v[132:135], off
	ds_read_b128 v[84:87], v8 offset:13056
	ds_read_b128 v[88:91], v8 offset:13072
	s_waitcnt vmcnt(7)
	v_lshlrev_b32_e32 v124, 16, v64
	v_and_b32_e32 v125, 0xffff0000, v64
	v_lshlrev_b32_e32 v126, 16, v65
	v_and_b32_e32 v127, 0xffff0000, v65
	v_lshlrev_b32_e32 v128, 16, v66
	v_and_b32_e32 v129, 0xffff0000, v66
	v_lshlrev_b32_e32 v130, 16, v67
	v_and_b32_e32 v131, 0xffff0000, v67
	s_waitcnt lgkmcnt(2)
	v_pk_fma_f32 v[124:125], v[92:93], v[36:37], v[124:125]
	v_pk_fma_f32 v[126:127], v[94:95], v[38:39], v[126:127]
	v_pk_fma_f32 v[128:129], v[96:97], v[40:41], v[128:129]
	v_pk_fma_f32 v[130:131], v[98:99], v[42:43], v[130:131]
	v_cvt_pk_bf16_f32 v136, v124, v125
	v_cvt_pk_bf16_f32 v137, v126, v127
	v_cvt_pk_bf16_f32 v138, v128, v129
	v_cvt_pk_bf16_f32 v139, v130, v131
	global_store_dwordx4 v[110:111], v[136:139], off
	ds_read_b128 v[92:95], v8 offset:15232
	ds_read_b128 v[96:99], v8 offset:15248
	s_waitcnt vmcnt(7)
	v_lshlrev_b32_e32 v116, 16, v68
	v_and_b32_e32 v117, 0xffff0000, v68
	v_lshlrev_b32_e32 v118, 16, v69
	v_and_b32_e32 v119, 0xffff0000, v69
	v_lshlrev_b32_e32 v120, 16, v70
	v_and_b32_e32 v121, 0xffff0000, v70
	v_lshlrev_b32_e32 v122, 16, v71
	v_and_b32_e32 v123, 0xffff0000, v71
	s_waitcnt lgkmcnt(2)
	v_pk_fma_f32 v[116:117], v[84:85], v[36:37], v[116:117]
	v_pk_fma_f32 v[118:119], v[86:87], v[38:39], v[118:119]
	v_pk_fma_f32 v[120:121], v[88:89], v[40:41], v[120:121]
	v_pk_fma_f32 v[122:123], v[90:91], v[42:43], v[122:123]
	v_cvt_pk_bf16_f32 v132, v116, v117
	v_cvt_pk_bf16_f32 v133, v118, v119
	v_cvt_pk_bf16_f32 v134, v120, v121
	v_cvt_pk_bf16_f32 v135, v122, v123
	global_store_dwordx4 v[112:113], v[132:135], off
	s_waitcnt vmcnt(7)
	v_lshlrev_b32_e32 v124, 16, v72
	v_and_b32_e32 v125, 0xffff0000, v72
	v_lshlrev_b32_e32 v126, 16, v73
	v_and_b32_e32 v127, 0xffff0000, v73
	v_lshlrev_b32_e32 v128, 16, v74
	v_and_b32_e32 v129, 0xffff0000, v74
	v_lshlrev_b32_e32 v130, 16, v75
	v_and_b32_e32 v131, 0xffff0000, v75
	s_waitcnt lgkmcnt(0)
	v_pk_fma_f32 v[124:125], v[92:93], v[36:37], v[124:125]
	v_pk_fma_f32 v[126:127], v[94:95], v[38:39], v[126:127]
	v_pk_fma_f32 v[128:129], v[96:97], v[40:41], v[128:129]
	v_pk_fma_f32 v[130:131], v[98:99], v[42:43], v[130:131]
	v_cvt_pk_bf16_f32 v136, v124, v125
	v_cvt_pk_bf16_f32 v137, v126, v127
	v_cvt_pk_bf16_f32 v138, v128, v129
	v_cvt_pk_bf16_f32 v139, v130, v131
	global_store_dwordx4 v[114:115], v[136:139], off
